# W_pg weight copy (256 items) moved out of the P1 tail: converted at the start of P2 by waves 0-3 of the 64 class-0 workgroups (re-entering the tail loop once); P1 third round shrinks to 64 items
# speedup vs baseline: 1.0051x; 1.0008x over previous
; __global__ void __launch_bounds__(NWAVES * 64, 2) fwd_kernel(Args args) {
;     ...
;     const int tid = threadIdx.x, wave = __builtin_amdgcn_readfirstlane(tid >> 6);
;     const int G = gridDim.x, bx = blockIdx.x;
;     const int vcu = (G % 8 == 0) ? (bx % 8) * (G / 8) + bx / 8 : bx;
_Z10fwd_kernel4Args:
	s_mov_b32 s100, 0
	s_load_dword s69, s[0:1], 0xa8
	s_mov_b32 s10, s2
	s_add_u32 s2, s0, 0xa8
	s_addc_u32 s3, s1, 0
	v_readfirstlane_b32 s11, v0
	v_writelane_b32 v254, s2, 0
	s_mov_b32 s85, s10
	s_nop 0
	v_writelane_b32 v254, s3, 1
	s_waitcnt lgkmcnt(0)
	s_and_b32 s2, s69, 7
	s_cmp_lg_u32 s2, 0
	s_cbranch_scc1 .LBB0_2
	s_ashr_i32 s3, s10, 31
	s_lshr_b32 s3, s3, 29
	s_add_i32 s3, s10, s3
	s_and_b32 s4, s3, -8
	s_ashr_i32 s2, s69, 3
	s_sub_i32 s4, s10, s4
	s_mul_i32 s2, s2, s4
	s_ashr_i32 s3, s3, 3
	s_add_i32 s85, s2, s3

; __device__ __forceinline__ unsigned xb_add(unsigned* p, unsigned v) { return __hip_atomic_fetch_add(p, v, __ATOMIC_RELAXED, __HIP_MEMORY_SCOPE_AGENT); }
; __device__ __forceinline__ void grp_barrier(unsigned* cntw, unsigned* tmo) {
;     asm volatile("s_waitcnt vmcnt(0)" ::: "memory");
;     __syncthreads();
;     if (threadIdx.x == 0) {
;         __builtin_amdgcn_s_waitcnt(0);
;         asm volatile("buffer_inv sc1" ::: "memory");
;         const unsigned old = xb_add(cntw, 1u);
;         const unsigned target = (old / 32u + 1u) * 32u;
.LBB0_453:
	s_cmp_gt_i32 s77, 2
	s_cselect_b64 s[0:1], -1, 0
	s_and_b64 s[2:3], s[14:15], s[0:1]
	v_readlane_b32 s90, v254, 18
	s_andn2_b64 vcc, exec, s[2:3]
	v_readlane_b32 s91, v254, 19
	s_cbranch_vccnz .LBB0_524
	s_cmp_lg_u32 s100, 0
	s_cbranch_scc1 .LBB0_524
	s_add_i32 s2, 0, 0x20170
	v_mov_b32_e32 v2, s2
	ds_read_b32 v2, v2
	s_waitcnt lgkmcnt(0)
	v_cmp_eq_u32_e32 vcc, 0, v2
	s_cbranch_vccnz .LBB0_467
	s_waitcnt vmcnt(0)
	s_barrier
	s_and_saveexec_b64 s[2:3], s[92:93]
	s_cbranch_execz .LBB0_472
	s_lshl_b32 s4, s10, 8
	s_and_b32 s4, s4, 0x700
	s_mov_b64 s[6:7], exec
	s_add_u32 s4, s22, s4
	s_addc_u32 s5, s23, 0
	s_waitcnt vmcnt(0) expcnt(0) lgkmcnt(0)
	buffer_inv sc1
	v_mbcnt_lo_u32_b32 v2, s6, 0
	s_add_u32 s4, s4, 0x2800
	v_mbcnt_hi_u32_b32 v3, s7, v2
	s_addc_u32 s5, s5, 0
	v_cmp_eq_u32_e32 vcc, 0, v3
	s_and_saveexec_b64 s[8:9], vcc
	s_cbranch_execz .LBB0_458
	s_bcnt1_i32_b64 s6, s[6:7]
	v_mov_b32_e32 v2, 0
	v_mov_b32_e32 v4, s6
	global_atomic_add v4, v2, v4, s[4:5] sc0

; __device__ __forceinline__ void convert_weights(const Args& args, int first, int last, int worker, int nworkers, int lane) {
;     int it = first + worker;
;     if (it >= last) return;
; __global__ void __launch_bounds__(NWAVES * 64, 2) fwd_kernel(Args args) {
;     ...
;         for (int v = vcu; v < nattn; v += G) {
;             const int bh = v >> 2, s = v & 3;
;             for (int i = 0; i < 2; ++i) {
;                 const int qb = i == 0 ? s : 7 - s;
;                 attn_body::attn_unit<8>(bh / NHEAD, bh % NHEAD, qb, MIX + AW, Kb, Vb, (dry ? dmy_mix : MIX) + AW, kms, (char*)lds_raw);
.LBB0_523:
.LBB0_524:
	s_cmp_lg_u32 s100, 0
	s_cbranch_scc1 .Lw_done
	s_and_b64 vcc, exec, s[88:89]
	s_cbranch_vccz .Lw_done
	s_and_b32 s98, s85, 3
	s_cmp_lg_u32 s98, 0
	s_cbranch_scc1 .Lw_done
	v_readlane_b32 s98, v254, 22
	s_nop 0
	s_cmp_gt_u32 s98, 3
	s_cbranch_scc1 .Lw_done
	s_lshr_b32 s25, s85, 2
	s_lshl_b32 s25, s25, 2
	s_add_i32 s25, s25, s98
	s_addk_i32 s25, 0x840
	s_mov_b32 s100, 1
	s_branch .Lw_go
